# attention loops: dead halves of packed row-sum removed, +0 chain start folded, leftover canonicalising max folded, back-edge branch pair merged
# speedup vs baseline: 1.0033x; 1.0033x over previous
.LBB0_934:
	s_or_b64 exec, exec, s[8:9]
	v_add3_u32 v64, s18, v190, v168
	ds_read_b128 v[32:35], v64
	ds_read_b128 v[36:39], v64 offset:0x1a00
	ds_read_b128 v[40:43], v64 offset:32
	ds_read_b128 v[44:47], v64 offset:0x1a20
	ds_read_b128 v[136:139], v64 offset:64
	ds_read_b128 v[140:143], v64 offset:0x1a40
	ds_read_b128 v[144:147], v64 offset:96
	ds_read_b128 v[148:151], v64 offset:0x1a60
	ds_read_b128 v[152:155], v64 offset:128
	ds_read_b128 v[156:159], v64 offset:0x1a80
	ds_read_b128 v[206:209], v64 offset:160
	ds_read_b128 v[160:163], v64 offset:0x1aa0
	s_nop 0
	s_waitcnt lgkmcnt(11)
	v_mfma_f32_32x32x16_bf16 v[80:95], v[32:35], v[116:119], v[48:63]
	v_add_u32_e32 v32, s18, v191
	v_add3_u32 v32, v32, v189, s87
	s_waitcnt lgkmcnt(10)
	v_mfma_f32_32x32x16_bf16 v[64:79], v[36:39], v[116:119], v[48:63]
	s_waitcnt lgkmcnt(9)
	v_mfma_f32_32x32x16_bf16 v[80:95], v[40:43], v[112:115], v[80:95]
	s_waitcnt lgkmcnt(8)
	v_mfma_f32_32x32x16_bf16 v[64:79], v[44:47], v[112:115], v[64:79]
	s_waitcnt lgkmcnt(7)
	v_mfma_f32_32x32x16_bf16 v[80:95], v[136:139], v[108:111], v[80:95]
	s_waitcnt lgkmcnt(6)
	v_mfma_f32_32x32x16_bf16 v[64:79], v[140:143], v[108:111], v[64:79]
	s_waitcnt lgkmcnt(5)
	v_mfma_f32_32x32x16_bf16 v[80:95], v[144:147], v[104:107], v[80:95]
	s_waitcnt lgkmcnt(4)
	v_mfma_f32_32x32x16_bf16 v[64:79], v[148:151], v[104:107], v[64:79]
	s_waitcnt lgkmcnt(3)
	v_mfma_f32_32x32x16_bf16 v[80:95], v[152:155], v[100:103], v[80:95]
	s_waitcnt lgkmcnt(2)
	v_mfma_f32_32x32x16_bf16 v[64:79], v[156:159], v[100:103], v[64:79]
	s_waitcnt lgkmcnt(0)
	v_mfma_f32_32x32x16_bf16 v[64:79], v[160:163], v[96:99], v[64:79]
	ds_read_b64 v[164:165], v32
	ds_read_b64 v[166:167], v32 offset:16
	ds_read_b64 v[160:161], v32 offset:32
	ds_read_b64 v[162:163], v32 offset:48
	ds_read_b64 v[156:157], v32 offset:64
	ds_read_b64 v[158:159], v32 offset:80
	ds_read_b64 v[152:153], v32 offset:96
	ds_read_b64 v[154:155], v32 offset:112
	ds_read_b64 v[148:149], v32 offset:0x1100
	ds_read_b64 v[150:151], v32 offset:0x1110
	ds_read_b64 v[144:145], v32 offset:0x1120
	ds_read_b64 v[146:147], v32 offset:0x1130
	ds_read_b64 v[140:141], v32 offset:0x1140
	ds_read_b64 v[142:143], v32 offset:0x1150
	ds_read_b64 v[136:137], v32 offset:0x1160
	ds_read_b64 v[138:139], v32 offset:0x1170
	v_mfma_f32_32x32x16_bf16 v[80:95], v[206:209], v[96:99], v[80:95]
	s_nop 11
	v_max_f32_e32 v32, v80, v64
	v_max_f32_e32 v33, v81, v65
	v_max_f32_e32 v34, v83, v67
	v_max3_f32 v34, v82, v66, v34
	v_max3_f32 v32, v32, v33, v34
	v_max_f32_e32 v33, v85, v69
	v_max_f32_e32 v34, v87, v71
	v_max3_f32 v33, v84, v68, v33
	v_max3_f32 v34, v86, v70, v34
	v_max3_f32 v32, v32, v33, v34
	v_max_f32_e32 v33, v89, v73
	v_max_f32_e32 v34, v91, v75
	v_max3_f32 v33, v88, v72, v33
	v_max3_f32 v34, v90, v74, v34
	v_max3_f32 v32, v32, v33, v34
	v_max_f32_e32 v33, v93, v77
	v_max_f32_e32 v34, v95, v79
	v_max3_f32 v33, v92, v76, v33
	v_max3_f32 v34, v94, v78, v34
	v_max3_f32 v32, v32, v33, v34
	v_mov_b32_e32 v33, v32
	s_nop 1
	v_permlane32_swap_b32_e32 v32, v33
	v_max_f32_e32 v32, v32, v33
	v_cmp_lt_f32_e32 vcc, s80, v32
	s_cbranch_vccz .LBB0_936
	v_max_f32_e32 v48, 0, v32
	v_exp_f32_e64 v32, -v48
	s_nop 0
	v_mov_b32_e32 v49, v32
	v_pk_mul_f32 v[30:31], v[30:31], v[32:33] op_sel_hi:[1,0]
	v_pk_mul_f32 v[28:29], v[28:29], v[32:33] op_sel_hi:[1,0]
	v_pk_mul_f32 v[26:27], v[26:27], v[32:33] op_sel_hi:[1,0]
	v_pk_mul_f32 v[24:25], v[24:25], v[32:33] op_sel_hi:[1,0]
	v_pk_mul_f32 v[22:23], v[22:23], v[32:33] op_sel_hi:[1,0]
	v_pk_mul_f32 v[20:21], v[20:21], v[32:33] op_sel_hi:[1,0]
	v_pk_mul_f32 v[18:19], v[18:19], v[32:33] op_sel_hi:[1,0]
	v_pk_mul_f32 v[14:15], v[14:15], v[32:33] op_sel_hi:[1,0]
	v_pk_mul_f32 v[12:13], v[12:13], v[32:33] op_sel_hi:[1,0]
	v_pk_mul_f32 v[10:11], v[10:11], v[32:33] op_sel_hi:[1,0]
	v_pk_mul_f32 v[8:9], v[8:9], v[32:33] op_sel_hi:[1,0]
	v_pk_mul_f32 v[6:7], v[6:7], v[32:33] op_sel_hi:[1,0]
	v_pk_mul_f32 v[4:5], v[4:5], v[32:33] op_sel_hi:[1,0]
	v_pk_mul_f32 v[2:3], v[2:3], v[32:33] op_sel_hi:[1,0]
	v_pk_mul_f32 v[16:17], v[16:17], v[32:33] op_sel_hi:[1,0]
	v_pk_mul_f32 v[0:1], v[0:1], v[32:33] op_sel_hi:[1,0]
	v_pk_add_f32 v[178:179], v[176:177], v[48:49]
	v_pk_mul_f32 v[32:33], v[176:177], v[48:49]
	v_pk_add_f32 v[80:81], v[80:81], v[48:49] op_sel_hi:[1,0] neg_lo:[0,1] neg_hi:[0,1]
	v_mov_b32_e32 v179, v33
	v_pk_add_f32 v[32:33], v[178:179], 0 neg_lo:[1,1] neg_hi:[1,1]
	v_pk_add_f32 v[64:65], v[64:65], v[48:49] op_sel_hi:[1,0] neg_lo:[0,1] neg_hi:[0,1]
	v_pk_add_f32 v[82:83], v[82:83], v[48:49] op_sel_hi:[1,0] neg_lo:[0,1] neg_hi:[0,1]
	v_pk_add_f32 v[66:67], v[66:67], v[48:49] op_sel_hi:[1,0] neg_lo:[0,1] neg_hi:[0,1]
	v_pk_add_f32 v[84:85], v[84:85], v[48:49] op_sel_hi:[1,0] neg_lo:[0,1] neg_hi:[0,1]
	v_pk_add_f32 v[68:69], v[68:69], v[48:49] op_sel_hi:[1,0] neg_lo:[0,1] neg_hi:[0,1]
	v_pk_add_f32 v[86:87], v[86:87], v[48:49] op_sel_hi:[1,0] neg_lo:[0,1] neg_hi:[0,1]
	v_pk_add_f32 v[70:71], v[70:71], v[48:49] op_sel_hi:[1,0] neg_lo:[0,1] neg_hi:[0,1]
	v_pk_add_f32 v[88:89], v[88:89], v[48:49] op_sel_hi:[1,0] neg_lo:[0,1] neg_hi:[0,1]
	v_pk_add_f32 v[72:73], v[72:73], v[48:49] op_sel_hi:[1,0] neg_lo:[0,1] neg_hi:[0,1]
	v_pk_add_f32 v[90:91], v[90:91], v[48:49] op_sel_hi:[1,0] neg_lo:[0,1] neg_hi:[0,1]
	v_pk_add_f32 v[74:75], v[74:75], v[48:49] op_sel_hi:[1,0] neg_lo:[0,1] neg_hi:[0,1]
	v_pk_add_f32 v[92:93], v[92:93], v[48:49] op_sel_hi:[1,0] neg_lo:[0,1] neg_hi:[0,1]
	v_pk_add_f32 v[76:77], v[76:77], v[48:49] op_sel_hi:[1,0] neg_lo:[0,1] neg_hi:[0,1]
	v_mov_b32_e32 v33, v32
	v_mov_b32_e32 v34, v32
	v_mov_b32_e32 v35, v32
	v_mov_b32_e32 v36, v32
	v_mov_b32_e32 v37, v32
	v_mov_b32_e32 v38, v32
	v_mov_b32_e32 v39, v32
	v_mov_b32_e32 v40, v32
	v_mov_b32_e32 v41, v32
	v_mov_b32_e32 v42, v32
	v_mov_b32_e32 v43, v32
	v_mov_b32_e32 v44, v32
	v_mov_b32_e32 v45, v32
	v_mov_b32_e32 v46, v32
	v_mov_b32_e32 v47, v32
	v_pk_add_f32 v[94:95], v[94:95], v[48:49] op_sel_hi:[1,0] neg_lo:[0,1] neg_hi:[0,1]
	v_pk_add_f32 v[78:79], v[78:79], v[48:49] op_sel_hi:[1,0] neg_lo:[0,1] neg_hi:[0,1]
	v_mov_b32_e32 v48, v32
	v_mov_b32_e32 v49, v32
	v_mov_b32_e32 v50, v32
	v_mov_b32_e32 v51, v32
	v_mov_b32_e32 v52, v32
	v_mov_b32_e32 v53, v32
	v_mov_b32_e32 v54, v32
	v_mov_b32_e32 v55, v32
	v_mov_b32_e32 v56, v32
	v_mov_b32_e32 v57, v32
	v_mov_b32_e32 v58, v32
	v_mov_b32_e32 v59, v32
	v_mov_b32_e32 v60, v32
	v_mov_b32_e32 v61, v32
	v_mov_b32_e32 v62, v32
	v_mov_b32_e32 v63, v32
	v_mov_b32_e32 v176, v178
	s_branch .LBB0_937

.LBB0_937:
	v_exp_f32_e32 v80, v80
	v_exp_f32_e32 v81, v81
	v_exp_f32_e32 v82, v82
	v_exp_f32_e32 v83, v83
	v_exp_f32_e32 v84, v84
	v_exp_f32_e32 v85, v85
	v_exp_f32_e32 v86, v86
	v_exp_f32_e32 v87, v87
	v_exp_f32_e32 v206, v64
	v_exp_f32_e32 v207, v65
	v_exp_f32_e32 v208, v66
	v_exp_f32_e32 v209, v67
	v_cvt_pk_bf16_f32 v64, v80, v81
	v_cvt_pk_bf16_f32 v65, v82, v83
	v_cvt_pk_bf16_f32 v66, v84, v85
	v_cvt_pk_bf16_f32 v67, v86, v87
	s_waitcnt lgkmcnt(0)
	v_exp_f32_e32 v88, v88
	v_exp_f32_e32 v89, v89
	v_mfma_f32_32x32x16_bf16 v[0:15], v[164:167], v[64:67], v[0:15]
	v_exp_f32_e32 v90, v90
	v_exp_f32_e32 v91, v91
	v_exp_f32_e32 v92, v92
	v_exp_f32_e32 v93, v93
	v_exp_f32_e32 v94, v94
	v_exp_f32_e32 v95, v95
	v_exp_f32_e32 v210, v68
	v_mfma_f32_32x32x16_bf16 v[16:31], v[148:151], v[64:67], v[16:31]
	v_exp_f32_e32 v211, v69
	v_exp_f32_e32 v212, v70
	v_exp_f32_e32 v213, v71
	v_cvt_pk_bf16_f32 v68, v88, v89
	v_cvt_pk_bf16_f32 v69, v90, v91
	v_cvt_pk_bf16_f32 v70, v92, v93
	v_cvt_pk_bf16_f32 v71, v94, v95
	v_exp_f32_e32 v214, v72
	v_mfma_f32_32x32x16_bf16 v[0:15], v[160:163], v[68:71], v[0:15]
	v_exp_f32_e32 v215, v73
	v_exp_f32_e32 v160, v74
	v_exp_f32_e32 v161, v75
	v_cvt_pk_bf16_f32 v72, v206, v207
	v_cvt_pk_bf16_f32 v73, v208, v209
	v_cvt_pk_bf16_f32 v74, v210, v211
	v_cvt_pk_bf16_f32 v75, v212, v213
	v_mfma_f32_32x32x16_bf16 v[16:31], v[144:147], v[68:71], v[16:31]
	v_add_f32_e64 v64, v206, v80
	v_add_f32_e64 v65, v207, v81
	v_exp_f32_e32 v162, v76
	v_add_f32_e32 v64, v82, v64
	v_add_f32_e32 v65, v83, v65
	v_exp_f32_e32 v163, v77
	v_add_f32_e32 v64, v208, v64
	v_add_f32_e32 v65, v209, v65
	v_cvt_pk_bf16_f32 v76, v214, v215
	v_add_f32_e32 v64, v84, v64
	v_add_f32_e32 v65, v85, v65
	v_mfma_f32_32x32x16_bf16 v[0:15], v[156:159], v[72:75], v[0:15]
	v_exp_f32_e32 v156, v78
	v_exp_f32_e32 v157, v79
	v_add_f32_e32 v64, v210, v64
	v_add_f32_e32 v65, v211, v65
	v_cvt_pk_bf16_f32 v77, v160, v161
	v_add_f32_e32 v64, v86, v64
	v_add_f32_e32 v65, v87, v65
	v_cvt_pk_bf16_f32 v78, v162, v163
	v_add_f32_e32 v64, v212, v64
	v_add_f32_e32 v65, v213, v65
	v_mfma_f32_32x32x16_bf16 v[16:31], v[140:143], v[72:75], v[16:31]
	v_add_f32_e64 v64, v88, v64
	v_add_f32_e64 v65, v89, v65
	v_cvt_pk_bf16_f32 v79, v156, v157
	v_add_f32_e64 v64, v214, v64
	v_add_f32_e64 v65, v215, v65
	s_add_i32 s17, s17, 0x8000
	v_add_f32_e32 v64, v90, v64
	v_add_f32_e32 v65, v91, v65
	v_lshl_add_u64 v[170:171], v[170:171], 0, s[94:95]
	v_add_f32_e32 v64, v160, v64
	v_add_f32_e32 v65, v161, v65
	v_mfma_f32_32x32x16_bf16 v[0:15], v[152:155], v[76:79], v[0:15]
	v_add_f32_e64 v64, v92, v64
	v_add_f32_e64 v65, v93, v65
	v_lshl_add_u64 v[172:173], v[172:173], 0, s[96:97]
	v_add_f32_e64 v64, v162, v64
	v_add_f32_e64 v65, v163, v65
	s_cmp_lg_u32 s17, 0x118000
	v_add_f32_e32 v64, v94, v64
	v_add_f32_e32 v65, v95, v65
	v_lshl_add_u64 v[174:175], v[174:175], 0, s[96:97]
	v_add_f32_e32 v64, v156, v64
	v_add_f32_e32 v65, v157, v65
	v_mfma_f32_32x32x16_bf16 v[16:31], v[136:139], v[76:79], v[16:31]
	v_add_f32_e32 v64, v64, v65
	s_nop 0
	v_add_f32_e32 v136, v179, v64
	s_cbranch_scc0 .LBB0_939
	v_mov_b32_e32 v177, v136
	s_branch .LBB0_926

.LBB0_959:
	s_or_b64 exec, exec, s[0:1]
	v_lshl_add_u64 v[64:65], s[4:5], 0, v[206:207]
	v_add_co_u32_e32 v64, vcc, 0xa808000, v64
	v_add3_u32 v96, s29, v245, v204
	s_nop 0
	v_addc_co_u32_e32 v65, vcc, 0, v65, vcc
	global_load_dwordx4 v[152:155], v[64:65], off
	global_load_dwordx4 v[156:159], v[64:65], off offset:256
	ds_read_b128 v[64:67], v96
	ds_read_b128 v[68:71], v96 offset:0x1200
	ds_read_b128 v[72:75], v96 offset:32
	ds_read_b128 v[76:79], v96 offset:0x1220
	ds_read_b128 v[160:163], v96 offset:64
	ds_read_b128 v[164:167], v96 offset:0x1240
	ds_read_b128 v[168:171], v96 offset:96
	ds_read_b128 v[172:175], v96 offset:0x1260
	s_nop 0
	s_waitcnt lgkmcnt(7)
	v_mfma_f32_32x32x16_bf16 v[112:127], v[64:67], v[140:143], v[80:95]
	v_add_u32_e32 v64, s29, v246
	v_add3_u32 v247, v64, v244, s87
	s_waitcnt lgkmcnt(6)
	v_mfma_f32_32x32x16_bf16 v[96:111], v[68:71], v[140:143], v[80:95]
	s_waitcnt lgkmcnt(5)
	v_mfma_f32_32x32x16_bf16 v[112:127], v[72:75], v[136:139], v[112:127]
	s_waitcnt lgkmcnt(4)
	v_mfma_f32_32x32x16_bf16 v[96:111], v[76:79], v[136:139], v[96:111]
	s_waitcnt lgkmcnt(3)
	v_mfma_f32_32x32x16_bf16 v[112:127], v[160:163], v[132:135], v[112:127]
	s_waitcnt lgkmcnt(2)
	v_mfma_f32_32x32x16_bf16 v[96:111], v[164:167], v[132:135], v[96:111]
	s_waitcnt lgkmcnt(1)
	v_mfma_f32_32x32x16_bf16 v[112:127], v[168:171], v[128:131], v[112:127]
	s_waitcnt lgkmcnt(0)
	v_mfma_f32_32x32x16_bf16 v[96:111], v[172:175], v[128:131], v[96:111]
	s_nop 10
	ds_read_b64 v[188:189], v247
	ds_read_b64 v[190:191], v247 offset:16
	ds_read_b64 v[184:185], v247 offset:32
	ds_read_b64 v[186:187], v247 offset:48
	ds_read_b64 v[180:181], v247 offset:64
	ds_read_b64 v[182:183], v247 offset:80
	ds_read_b64 v[176:177], v247 offset:96
	ds_read_b64 v[178:179], v247 offset:112
	ds_read_b64 v[172:173], v247 offset:0x1100
	ds_read_b64 v[174:175], v247 offset:0x1110
	ds_read_b64 v[168:169], v247 offset:0x1120
	ds_read_b64 v[170:171], v247 offset:0x1130
	ds_read_b64 v[164:165], v247 offset:0x1140
	ds_read_b64 v[166:167], v247 offset:0x1150
	ds_read_b64 v[160:161], v247 offset:0x1160
	ds_read_b64 v[162:163], v247 offset:0x1170
	v_max_f32_e32 v64, v112, v96
	v_max_f32_e32 v65, v113, v97
	v_max_f32_e32 v66, v115, v99
	v_max3_f32 v66, v114, v98, v66
	v_max3_f32 v64, v64, v65, v66
	v_max_f32_e32 v65, v117, v101
	v_max_f32_e32 v66, v119, v103
	v_max3_f32 v65, v116, v100, v65
	v_max3_f32 v66, v118, v102, v66
	v_max3_f32 v64, v64, v65, v66
	v_max_f32_e32 v65, v121, v105
	v_max_f32_e32 v66, v123, v107
	v_max3_f32 v65, v120, v104, v65
	v_max3_f32 v66, v122, v106, v66
	v_max3_f32 v64, v64, v65, v66
	v_max_f32_e32 v65, v125, v109
	v_max_f32_e32 v66, v127, v111
	v_max3_f32 v65, v124, v108, v65
	v_max3_f32 v66, v126, v110, v66
	v_max3_f32 v64, v64, v65, v66
	v_mov_b32_e32 v65, v64
	s_nop 1
	v_permlane32_swap_b32_e32 v64, v65
	v_max_f32_e32 v64, v64, v65
	v_cmp_lt_f32_e32 vcc, s80, v64
	s_cbranch_vccz .LBB0_961
	v_max_f32_e32 v80, 0, v64
	v_exp_f32_e64 v64, -v80
	s_nop 0
	v_mov_b32_e32 v81, v64
	v_pk_mul_f32 v[14:15], v[14:15], v[64:65] op_sel_hi:[1,0]
	v_pk_mul_f32 v[12:13], v[12:13], v[64:65] op_sel_hi:[1,0]
	v_pk_mul_f32 v[10:11], v[10:11], v[64:65] op_sel_hi:[1,0]
	v_pk_mul_f32 v[8:9], v[8:9], v[64:65] op_sel_hi:[1,0]
	v_pk_mul_f32 v[6:7], v[6:7], v[64:65] op_sel_hi:[1,0]
	v_pk_mul_f32 v[4:5], v[4:5], v[64:65] op_sel_hi:[1,0]
	v_pk_mul_f32 v[2:3], v[2:3], v[64:65] op_sel_hi:[1,0]
	v_pk_mul_f32 v[0:1], v[0:1], v[64:65] op_sel_hi:[1,0]
	v_pk_mul_f32 v[30:31], v[30:31], v[64:65] op_sel_hi:[1,0]
	v_pk_mul_f32 v[28:29], v[28:29], v[64:65] op_sel_hi:[1,0]
	v_pk_mul_f32 v[26:27], v[26:27], v[64:65] op_sel_hi:[1,0]
	v_pk_mul_f32 v[24:25], v[24:25], v[64:65] op_sel_hi:[1,0]
	v_pk_mul_f32 v[22:23], v[22:23], v[64:65] op_sel_hi:[1,0]
	v_pk_mul_f32 v[20:21], v[20:21], v[64:65] op_sel_hi:[1,0]
	v_pk_mul_f32 v[18:19], v[18:19], v[64:65] op_sel_hi:[1,0]
	v_pk_mul_f32 v[16:17], v[16:17], v[64:65] op_sel_hi:[1,0]
	v_pk_mul_f32 v[62:63], v[62:63], v[64:65] op_sel_hi:[1,0]
	v_pk_mul_f32 v[60:61], v[60:61], v[64:65] op_sel_hi:[1,0]
	v_pk_mul_f32 v[58:59], v[58:59], v[64:65] op_sel_hi:[1,0]
	v_pk_mul_f32 v[56:57], v[56:57], v[64:65] op_sel_hi:[1,0]
	v_pk_mul_f32 v[54:55], v[54:55], v[64:65] op_sel_hi:[1,0]
	v_pk_mul_f32 v[52:53], v[52:53], v[64:65] op_sel_hi:[1,0]
	v_pk_mul_f32 v[50:51], v[50:51], v[64:65] op_sel_hi:[1,0]
	v_pk_mul_f32 v[48:49], v[48:49], v[64:65] op_sel_hi:[1,0]
	v_pk_mul_f32 v[46:47], v[46:47], v[64:65] op_sel_hi:[1,0]
	v_pk_mul_f32 v[44:45], v[44:45], v[64:65] op_sel_hi:[1,0]
	v_pk_mul_f32 v[42:43], v[42:43], v[64:65] op_sel_hi:[1,0]
	v_pk_mul_f32 v[40:41], v[40:41], v[64:65] op_sel_hi:[1,0]
	v_pk_mul_f32 v[38:39], v[38:39], v[64:65] op_sel_hi:[1,0]
	v_pk_mul_f32 v[36:37], v[36:37], v[64:65] op_sel_hi:[1,0]
	v_pk_mul_f32 v[34:35], v[34:35], v[64:65] op_sel_hi:[1,0]
	v_pk_mul_f32 v[32:33], v[32:33], v[64:65] op_sel_hi:[1,0]
	v_pk_add_f32 v[214:215], v[212:213], v[80:81]
	v_pk_mul_f32 v[64:65], v[212:213], v[80:81]
	v_pk_add_f32 v[112:113], v[112:113], v[80:81] op_sel_hi:[1,0] neg_lo:[0,1] neg_hi:[0,1]
	v_mov_b32_e32 v215, v65
	v_pk_add_f32 v[64:65], v[214:215], 0 neg_lo:[1,1] neg_hi:[1,1]
	v_pk_add_f32 v[96:97], v[96:97], v[80:81] op_sel_hi:[1,0] neg_lo:[0,1] neg_hi:[0,1]
	v_pk_add_f32 v[114:115], v[114:115], v[80:81] op_sel_hi:[1,0] neg_lo:[0,1] neg_hi:[0,1]
	v_pk_add_f32 v[98:99], v[98:99], v[80:81] op_sel_hi:[1,0] neg_lo:[0,1] neg_hi:[0,1]
	v_pk_add_f32 v[116:117], v[116:117], v[80:81] op_sel_hi:[1,0] neg_lo:[0,1] neg_hi:[0,1]
	v_pk_add_f32 v[100:101], v[100:101], v[80:81] op_sel_hi:[1,0] neg_lo:[0,1] neg_hi:[0,1]
	v_pk_add_f32 v[118:119], v[118:119], v[80:81] op_sel_hi:[1,0] neg_lo:[0,1] neg_hi:[0,1]
	v_pk_add_f32 v[102:103], v[102:103], v[80:81] op_sel_hi:[1,0] neg_lo:[0,1] neg_hi:[0,1]
	v_pk_add_f32 v[120:121], v[120:121], v[80:81] op_sel_hi:[1,0] neg_lo:[0,1] neg_hi:[0,1]
	v_pk_add_f32 v[104:105], v[104:105], v[80:81] op_sel_hi:[1,0] neg_lo:[0,1] neg_hi:[0,1]
	v_pk_add_f32 v[122:123], v[122:123], v[80:81] op_sel_hi:[1,0] neg_lo:[0,1] neg_hi:[0,1]
	v_pk_add_f32 v[106:107], v[106:107], v[80:81] op_sel_hi:[1,0] neg_lo:[0,1] neg_hi:[0,1]
	v_pk_add_f32 v[124:125], v[124:125], v[80:81] op_sel_hi:[1,0] neg_lo:[0,1] neg_hi:[0,1]
	v_pk_add_f32 v[108:109], v[108:109], v[80:81] op_sel_hi:[1,0] neg_lo:[0,1] neg_hi:[0,1]
	v_mov_b32_e32 v65, v64
	v_mov_b32_e32 v66, v64
	v_mov_b32_e32 v67, v64
	v_mov_b32_e32 v68, v64
	v_mov_b32_e32 v69, v64
	v_mov_b32_e32 v70, v64
	v_mov_b32_e32 v71, v64
	v_mov_b32_e32 v72, v64
	v_mov_b32_e32 v73, v64
	v_mov_b32_e32 v74, v64
	v_mov_b32_e32 v75, v64
	v_mov_b32_e32 v76, v64
	v_mov_b32_e32 v77, v64
	v_mov_b32_e32 v78, v64
	v_mov_b32_e32 v79, v64
	v_pk_add_f32 v[126:127], v[126:127], v[80:81] op_sel_hi:[1,0] neg_lo:[0,1] neg_hi:[0,1]
	v_pk_add_f32 v[110:111], v[110:111], v[80:81] op_sel_hi:[1,0] neg_lo:[0,1] neg_hi:[0,1]
	v_mov_b32_e32 v80, v64
	v_mov_b32_e32 v81, v64
	v_mov_b32_e32 v82, v64
	v_mov_b32_e32 v83, v64
	v_mov_b32_e32 v84, v64
	v_mov_b32_e32 v85, v64
	v_mov_b32_e32 v86, v64
	v_mov_b32_e32 v87, v64
	v_mov_b32_e32 v88, v64
	v_mov_b32_e32 v89, v64
	v_mov_b32_e32 v90, v64
	v_mov_b32_e32 v91, v64
	v_mov_b32_e32 v92, v64
	v_mov_b32_e32 v93, v64
	v_mov_b32_e32 v94, v64
	v_mov_b32_e32 v95, v64
	v_mov_b32_e32 v212, v214
	s_branch .LBB0_962

.LBB0_962:
	v_exp_f32_e32 v232, v112
	v_exp_f32_e32 v233, v113
	v_exp_f32_e32 v96, v96
	v_exp_f32_e32 v97, v97
	v_exp_f32_e32 v114, v114
	v_exp_f32_e32 v115, v115
	v_exp_f32_e32 v98, v98
	v_exp_f32_e32 v99, v99
	v_exp_f32_e32 v116, v116
	v_exp_f32_e32 v117, v117
	v_add_f32_e32 v112, v96, v232
	v_add_f32_e32 v113, v97, v233
	v_exp_f32_e32 v100, v100
	v_exp_f32_e32 v101, v101
	v_add_f32_e32 v112, v114, v112
	v_add_f32_e32 v113, v115, v113
	v_exp_f32_e32 v118, v118
	v_exp_f32_e32 v119, v119
	v_add_f32_e32 v112, v98, v112
	v_add_f32_e32 v113, v99, v113
	v_exp_f32_e32 v102, v102
	v_exp_f32_e32 v103, v103
	v_add_f32_e32 v112, v116, v112
	v_add_f32_e32 v113, v117, v113
	v_exp_f32_e32 v120, v120
	v_exp_f32_e32 v121, v121
	v_add_f32_e32 v112, v100, v112
	v_add_f32_e32 v113, v101, v113
	v_exp_f32_e32 v248, v104
	v_exp_f32_e32 v249, v105
	v_add_f32_e32 v112, v118, v112
	v_add_f32_e32 v113, v119, v113
	v_exp_f32_e32 v122, v122
	v_exp_f32_e32 v123, v123
	v_add_f32_e32 v112, v102, v112
	v_add_f32_e32 v113, v103, v113
	v_exp_f32_e32 v250, v106
	v_exp_f32_e32 v251, v107
	v_add_f32_e32 v104, v120, v112
	v_add_f32_e32 v105, v121, v113
	v_exp_f32_e32 v106, v124
	v_exp_f32_e32 v107, v125
	v_exp_f32_e32 v124, v108
	v_exp_f32_e32 v125, v109
	v_exp_f32_e32 v252, v110
	v_exp_f32_e32 v253, v111
	v_cvt_pk_bf16_f32 v108, v232, v233
	v_cvt_pk_bf16_f32 v109, v114, v115
	v_cvt_pk_bf16_f32 v110, v116, v117
	v_cvt_pk_bf16_f32 v111, v118, v119
	v_add_f32_e32 v104, v248, v104
	v_add_f32_e32 v105, v249, v105
	s_waitcnt lgkmcnt(0)
	v_exp_f32_e32 v126, v126
	v_mfma_f32_32x32x16_bf16 v[0:15], v[188:191], v[108:111], v[0:15]
	v_add_f32_e64 v104, v122, v104
	v_add_f32_e64 v105, v123, v105
	v_exp_f32_e32 v127, v127
	v_add_f32_e32 v104, v250, v104
	v_add_f32_e32 v105, v251, v105
	v_cvt_pk_bf16_f32 v96, v96, v97
	v_add_f32_e32 v104, v106, v104
	v_add_f32_e32 v105, v107, v105
	v_cvt_pk_bf16_f32 v106, v106, v107
	v_add_f32_e32 v104, v124, v104
	v_add_f32_e32 v105, v125, v105
	v_mfma_f32_32x32x16_bf16 v[16:31], v[172:175], v[108:111], v[16:31]
	v_add_f32_e64 v104, v126, v104
	v_add_f32_e64 v105, v127, v105
	v_cvt_pk_bf16_f32 v107, v126, v127
	v_add_f32_e64 v104, v252, v104
	v_add_f32_e64 v105, v253, v105
	v_cvt_pk_bf16_f32 v97, v98, v99
	v_add_f32_e32 v112, v104, v105
	v_cvt_pk_bf16_f32 v104, v120, v121
	v_cvt_pk_bf16_f32 v105, v122, v123
	v_cvt_pk_bf16_f32 v98, v100, v101
	v_cvt_pk_bf16_f32 v99, v102, v103
	v_mfma_f32_32x32x16_bf16 v[0:15], v[184:187], v[104:107], v[0:15]
	v_cvt_pk_bf16_f32 v100, v248, v249
	v_cvt_pk_bf16_f32 v101, v250, v251
	v_cvt_pk_bf16_f32 v102, v124, v125
	v_cvt_pk_bf16_f32 v103, v252, v253
	v_add_u32_e32 v126, 0x2200, v247
	s_add_i32 s28, s28, 0x8000
	v_lshl_add_u64 v[206:207], v[206:207], 0, s[70:71]
	v_mfma_f32_32x32x16_bf16 v[16:31], v[168:171], v[104:107], v[16:31]
	v_lshl_add_u64 v[208:209], v[208:209], 0, s[94:95]
	v_lshl_add_u64 v[210:211], v[210:211], 0, s[94:95]
	s_cmp_lg_u32 s28, 0x118000
	v_mfma_f32_32x32x16_bf16 v[0:15], v[180:183], v[96:99], v[0:15]
	v_mfma_f32_32x32x16_bf16 v[16:31], v[164:167], v[96:99], v[16:31]
	v_mfma_f32_32x32x16_bf16 v[0:15], v[176:179], v[100:103], v[0:15]
	v_mfma_f32_32x32x16_bf16 v[16:31], v[160:163], v[100:103], v[16:31]
	ds_read_b64 v[176:177], v126
	ds_read_b64 v[178:179], v126 offset:16
	ds_read_b64 v[172:173], v126 offset:32
	ds_read_b64 v[174:175], v126 offset:48
	ds_read_b64 v[168:169], v126 offset:64
	ds_read_b64 v[170:171], v126 offset:80
	ds_read_b64 v[164:165], v126 offset:96
	ds_read_b64 v[166:167], v126 offset:112
	ds_read_b64 v[160:161], v126 offset:0x1100
	ds_read_b64 v[162:163], v126 offset:0x1110
	ds_read_b64 v[122:123], v126 offset:0x1120
	ds_read_b64 v[124:125], v126 offset:0x1130
	ds_read_b64 v[118:119], v126 offset:0x1140
	ds_read_b64 v[120:121], v126 offset:0x1150
	ds_read_b64 v[114:115], v126 offset:0x1160
	ds_read_b64 v[116:117], v126 offset:0x1170
	s_nop 0
	s_nop 0
	s_waitcnt lgkmcnt(14)
	v_mfma_f32_32x32x16_bf16 v[48:63], v[176:179], v[108:111], v[48:63]
	s_waitcnt lgkmcnt(6)
	v_mfma_f32_32x32x16_bf16 v[32:47], v[160:163], v[108:111], v[32:47]
	v_add_f32_e64 v160, v215, v112
	v_mfma_f32_32x32x16_bf16 v[48:63], v[172:175], v[104:107], v[48:63]
	s_waitcnt lgkmcnt(4)
	v_mfma_f32_32x32x16_bf16 v[32:47], v[122:125], v[104:107], v[32:47]
	v_mfma_f32_32x32x16_bf16 v[48:63], v[168:171], v[96:99], v[48:63]
	s_waitcnt lgkmcnt(2)
	v_mfma_f32_32x32x16_bf16 v[32:47], v[118:121], v[96:99], v[32:47]
	v_mfma_f32_32x32x16_bf16 v[48:63], v[164:167], v[100:103], v[48:63]
	s_waitcnt lgkmcnt(0)
	v_mfma_f32_32x32x16_bf16 v[32:47], v[114:117], v[100:103], v[32:47]
	v_mov_b32_e32 v213, v160
	s_cbranch_scc1 .LBB0_955

.LBB0_979:
	s_or_b64 exec, exec, s[0:1]
	v_lshl_add_u64 v[64:65], s[4:5], 0, v[204:205]
	v_add_co_u32_e32 v64, vcc, 0xa808000, v64
	v_add3_u32 v96, s9, v246, v192
	s_nop 0
	v_addc_co_u32_e32 v65, vcc, 0, v65, vcc
	global_load_dwordx4 v[152:155], v[64:65], off
	global_load_dwordx4 v[156:159], v[64:65], off offset:256
	ds_read_b128 v[64:67], v96
	ds_read_b128 v[68:71], v96 offset:0x1200
	ds_read_b128 v[72:75], v96 offset:32
	ds_read_b128 v[76:79], v96 offset:0x1220
	ds_read_b128 v[160:163], v96 offset:64
	ds_read_b128 v[164:167], v96 offset:0x1240
	ds_read_b128 v[168:171], v96 offset:96
	ds_read_b128 v[172:175], v96 offset:0x1260
	v_mov_b32_e32 v254, 0xc00
	s_waitcnt lgkmcnt(7)
	v_mfma_f32_32x32x16_bf16 v[112:127], v[64:67], v[140:143], v[80:95]
	v_add_u32_e32 v64, s9, v247
	v_add3_u32 v249, v64, v244, s87
	s_waitcnt lgkmcnt(6)
	v_mfma_f32_32x32x16_bf16 v[96:111], v[68:71], v[140:143], v[80:95]
	s_waitcnt lgkmcnt(5)
	v_mfma_f32_32x32x16_bf16 v[112:127], v[72:75], v[136:139], v[112:127]
	s_waitcnt lgkmcnt(4)
	v_mfma_f32_32x32x16_bf16 v[96:111], v[76:79], v[136:139], v[96:111]
	s_waitcnt lgkmcnt(3)
	v_mfma_f32_32x32x16_bf16 v[112:127], v[160:163], v[132:135], v[112:127]
	s_waitcnt lgkmcnt(2)
	v_mfma_f32_32x32x16_bf16 v[96:111], v[164:167], v[132:135], v[96:111]
	s_waitcnt lgkmcnt(1)
	v_mfma_f32_32x32x16_bf16 v[112:127], v[168:171], v[128:131], v[112:127]
	s_waitcnt lgkmcnt(0)
	v_mfma_f32_32x32x16_bf16 v[96:111], v[172:175], v[128:131], v[96:111]
	s_nop 10
	ds_read_b64 v[188:189], v249
	ds_read_b64 v[190:191], v249 offset:16
	ds_read_b64 v[184:185], v249 offset:32
	ds_read_b64 v[186:187], v249 offset:48
	ds_read_b64 v[180:181], v249 offset:64
	ds_read_b64 v[182:183], v249 offset:80
	ds_read_b64 v[176:177], v249 offset:96
	ds_read_b64 v[178:179], v249 offset:112
	ds_read_b64 v[172:173], v249 offset:0x1100
	ds_read_b64 v[174:175], v249 offset:0x1110
	ds_read_b64 v[168:169], v249 offset:0x1120
	ds_read_b64 v[170:171], v249 offset:0x1130
	ds_read_b64 v[164:165], v249 offset:0x1140
	ds_read_b64 v[166:167], v249 offset:0x1150
	ds_read_b64 v[160:161], v249 offset:0x1160
	ds_read_b64 v[162:163], v249 offset:0x1170
	v_max_f32_e32 v64, v112, v96
	v_max_f32_e32 v65, v113, v97
	v_max_f32_e32 v66, v115, v99
	v_max3_f32 v66, v114, v98, v66
	v_max3_f32 v64, v64, v65, v66
	v_max_f32_e32 v65, v117, v101
	v_max_f32_e32 v66, v119, v103
	v_max3_f32 v65, v116, v100, v65
	v_max3_f32 v66, v118, v102, v66
	v_max3_f32 v64, v64, v65, v66
	v_max_f32_e32 v65, v121, v105
	v_max_f32_e32 v66, v123, v107
	v_max3_f32 v65, v120, v104, v65
	v_max3_f32 v66, v122, v106, v66
	v_max3_f32 v64, v64, v65, v66
	v_max_f32_e32 v65, v125, v109
	v_max_f32_e32 v66, v127, v111
	v_max3_f32 v65, v124, v108, v65
	v_max3_f32 v66, v126, v110, v66
	v_max3_f32 v64, v64, v65, v66
	v_mov_b32_e32 v65, v64
	s_nop 1
	v_permlane32_swap_b32_e32 v64, v65
	v_max_f32_e32 v64, v64, v65
	v_cmp_lt_f32_e32 vcc, s80, v64
	s_cbranch_vccz .LBB0_981
	v_max_f32_e32 v80, 0, v64
	v_exp_f32_e64 v64, -v80
	s_nop 0
	v_mov_b32_e32 v81, v64
	v_pk_mul_f32 v[14:15], v[14:15], v[64:65] op_sel_hi:[1,0]
	v_pk_mul_f32 v[12:13], v[12:13], v[64:65] op_sel_hi:[1,0]
	v_pk_mul_f32 v[10:11], v[10:11], v[64:65] op_sel_hi:[1,0]
	v_pk_mul_f32 v[8:9], v[8:9], v[64:65] op_sel_hi:[1,0]
	v_pk_mul_f32 v[6:7], v[6:7], v[64:65] op_sel_hi:[1,0]
	v_pk_mul_f32 v[4:5], v[4:5], v[64:65] op_sel_hi:[1,0]
	v_pk_mul_f32 v[2:3], v[2:3], v[64:65] op_sel_hi:[1,0]
	v_pk_mul_f32 v[0:1], v[0:1], v[64:65] op_sel_hi:[1,0]
	v_pk_mul_f32 v[62:63], v[62:63], v[64:65] op_sel_hi:[1,0]
	v_pk_mul_f32 v[60:61], v[60:61], v[64:65] op_sel_hi:[1,0]
	v_pk_mul_f32 v[58:59], v[58:59], v[64:65] op_sel_hi:[1,0]
	v_pk_mul_f32 v[56:57], v[56:57], v[64:65] op_sel_hi:[1,0]
	v_pk_mul_f32 v[54:55], v[54:55], v[64:65] op_sel_hi:[1,0]
	v_pk_mul_f32 v[52:53], v[52:53], v[64:65] op_sel_hi:[1,0]
	v_pk_mul_f32 v[50:51], v[50:51], v[64:65] op_sel_hi:[1,0]
	v_pk_mul_f32 v[48:49], v[48:49], v[64:65] op_sel_hi:[1,0]
	v_pk_mul_f32 v[46:47], v[46:47], v[64:65] op_sel_hi:[1,0]
	v_pk_mul_f32 v[44:45], v[44:45], v[64:65] op_sel_hi:[1,0]
	v_pk_mul_f32 v[42:43], v[42:43], v[64:65] op_sel_hi:[1,0]
	v_pk_mul_f32 v[40:41], v[40:41], v[64:65] op_sel_hi:[1,0]
	v_pk_mul_f32 v[38:39], v[38:39], v[64:65] op_sel_hi:[1,0]
	v_pk_mul_f32 v[36:37], v[36:37], v[64:65] op_sel_hi:[1,0]
	v_pk_mul_f32 v[34:35], v[34:35], v[64:65] op_sel_hi:[1,0]
	v_pk_mul_f32 v[32:33], v[32:33], v[64:65] op_sel_hi:[1,0]
	v_pk_mul_f32 v[30:31], v[30:31], v[64:65] op_sel_hi:[1,0]
	v_pk_mul_f32 v[28:29], v[28:29], v[64:65] op_sel_hi:[1,0]
	v_pk_mul_f32 v[26:27], v[26:27], v[64:65] op_sel_hi:[1,0]
	v_pk_mul_f32 v[24:25], v[24:25], v[64:65] op_sel_hi:[1,0]
	v_pk_mul_f32 v[22:23], v[22:23], v[64:65] op_sel_hi:[1,0]
	v_pk_mul_f32 v[20:21], v[20:21], v[64:65] op_sel_hi:[1,0]
	v_pk_mul_f32 v[18:19], v[18:19], v[64:65] op_sel_hi:[1,0]
	v_pk_mul_f32 v[16:17], v[16:17], v[64:65] op_sel_hi:[1,0]
	v_pk_add_f32 v[212:213], v[210:211], v[80:81]
	v_pk_mul_f32 v[64:65], v[210:211], v[80:81]
	v_pk_add_f32 v[112:113], v[112:113], v[80:81] op_sel_hi:[1,0] neg_lo:[0,1] neg_hi:[0,1]
	v_mov_b32_e32 v213, v65
	v_pk_add_f32 v[64:65], v[212:213], 0 neg_lo:[1,1] neg_hi:[1,1]
	v_pk_add_f32 v[96:97], v[96:97], v[80:81] op_sel_hi:[1,0] neg_lo:[0,1] neg_hi:[0,1]
	v_pk_add_f32 v[114:115], v[114:115], v[80:81] op_sel_hi:[1,0] neg_lo:[0,1] neg_hi:[0,1]
	v_pk_add_f32 v[98:99], v[98:99], v[80:81] op_sel_hi:[1,0] neg_lo:[0,1] neg_hi:[0,1]
	v_pk_add_f32 v[116:117], v[116:117], v[80:81] op_sel_hi:[1,0] neg_lo:[0,1] neg_hi:[0,1]
	v_pk_add_f32 v[100:101], v[100:101], v[80:81] op_sel_hi:[1,0] neg_lo:[0,1] neg_hi:[0,1]
	v_pk_add_f32 v[118:119], v[118:119], v[80:81] op_sel_hi:[1,0] neg_lo:[0,1] neg_hi:[0,1]
	v_pk_add_f32 v[102:103], v[102:103], v[80:81] op_sel_hi:[1,0] neg_lo:[0,1] neg_hi:[0,1]
	v_pk_add_f32 v[120:121], v[120:121], v[80:81] op_sel_hi:[1,0] neg_lo:[0,1] neg_hi:[0,1]
	v_pk_add_f32 v[104:105], v[104:105], v[80:81] op_sel_hi:[1,0] neg_lo:[0,1] neg_hi:[0,1]
	v_pk_add_f32 v[122:123], v[122:123], v[80:81] op_sel_hi:[1,0] neg_lo:[0,1] neg_hi:[0,1]
	v_pk_add_f32 v[106:107], v[106:107], v[80:81] op_sel_hi:[1,0] neg_lo:[0,1] neg_hi:[0,1]
	v_pk_add_f32 v[124:125], v[124:125], v[80:81] op_sel_hi:[1,0] neg_lo:[0,1] neg_hi:[0,1]
	v_pk_add_f32 v[108:109], v[108:109], v[80:81] op_sel_hi:[1,0] neg_lo:[0,1] neg_hi:[0,1]
	v_mov_b32_e32 v65, v64
	v_mov_b32_e32 v66, v64
	v_mov_b32_e32 v67, v64
	v_mov_b32_e32 v68, v64
	v_mov_b32_e32 v69, v64
	v_mov_b32_e32 v70, v64
	v_mov_b32_e32 v71, v64
	v_mov_b32_e32 v72, v64
	v_mov_b32_e32 v73, v64
	v_mov_b32_e32 v74, v64
	v_mov_b32_e32 v75, v64
	v_mov_b32_e32 v76, v64
	v_mov_b32_e32 v77, v64
	v_mov_b32_e32 v78, v64
	v_mov_b32_e32 v79, v64
	v_pk_add_f32 v[126:127], v[126:127], v[80:81] op_sel_hi:[1,0] neg_lo:[0,1] neg_hi:[0,1]
	v_pk_add_f32 v[110:111], v[110:111], v[80:81] op_sel_hi:[1,0] neg_lo:[0,1] neg_hi:[0,1]
	v_mov_b32_e32 v80, v64
	v_mov_b32_e32 v81, v64
	v_mov_b32_e32 v82, v64
	v_mov_b32_e32 v83, v64
	v_mov_b32_e32 v84, v64
	v_mov_b32_e32 v85, v64
	v_mov_b32_e32 v86, v64
	v_mov_b32_e32 v87, v64
	v_mov_b32_e32 v88, v64
	v_mov_b32_e32 v89, v64
	v_mov_b32_e32 v90, v64
	v_mov_b32_e32 v91, v64
	v_mov_b32_e32 v92, v64
	v_mov_b32_e32 v93, v64
	v_mov_b32_e32 v94, v64
	v_mov_b32_e32 v95, v64
	v_mov_b32_e32 v210, v212
	s_branch .LBB0_982

.LBB0_982:
	v_exp_f32_e32 v232, v112
	v_exp_f32_e32 v233, v113
	v_exp_f32_e32 v96, v96
	v_exp_f32_e32 v97, v97
	v_exp_f32_e32 v114, v114
	v_exp_f32_e32 v115, v115
	v_exp_f32_e32 v98, v98
	v_exp_f32_e32 v99, v99
	v_exp_f32_e32 v116, v116
	v_exp_f32_e32 v117, v117
	v_add_f32_e32 v112, v96, v232
	v_add_f32_e32 v113, v97, v233
	v_exp_f32_e32 v100, v100
	v_exp_f32_e32 v101, v101
	v_add_f32_e32 v112, v114, v112
	v_add_f32_e32 v113, v115, v113
	v_exp_f32_e32 v118, v118
	v_exp_f32_e32 v119, v119
	v_add_f32_e32 v112, v98, v112
	v_add_f32_e32 v113, v99, v113
	v_exp_f32_e32 v102, v102
	v_exp_f32_e32 v103, v103
	v_add_f32_e32 v112, v116, v112
	v_add_f32_e32 v113, v117, v113
	v_exp_f32_e32 v120, v120
	v_exp_f32_e32 v121, v121
	v_add_f32_e32 v112, v100, v112
	v_add_f32_e32 v113, v101, v113
	v_exp_f32_e32 v250, v104
	v_exp_f32_e32 v251, v105
	v_add_f32_e32 v112, v118, v112
	v_add_f32_e32 v113, v119, v113
	v_exp_f32_e32 v122, v122
	v_exp_f32_e32 v123, v123
	v_add_f32_e32 v112, v102, v112
	v_add_f32_e32 v113, v103, v113
	v_exp_f32_e32 v252, v106
	v_exp_f32_e32 v253, v107
	v_add_f32_e32 v104, v120, v112
	v_add_f32_e32 v105, v121, v113
	v_exp_f32_e32 v106, v124
	v_exp_f32_e32 v107, v125
	v_exp_f32_e32 v124, v108
	v_exp_f32_e32 v125, v109
	v_exp_f32_e32 v234, v110
	v_exp_f32_e32 v235, v111
	v_cvt_pk_bf16_f32 v108, v232, v233
	v_cvt_pk_bf16_f32 v109, v114, v115
	v_cvt_pk_bf16_f32 v110, v116, v117
	v_cvt_pk_bf16_f32 v111, v118, v119
	v_add_f32_e32 v104, v250, v104
	v_add_f32_e32 v105, v251, v105
	s_waitcnt lgkmcnt(0)
	v_exp_f32_e32 v126, v126
	v_mfma_f32_32x32x16_bf16 v[0:15], v[188:191], v[108:111], v[0:15]
	v_add_f32_e64 v104, v122, v104
	v_add_f32_e64 v105, v123, v105
	v_exp_f32_e32 v127, v127
	v_add_f32_e32 v104, v252, v104
	v_add_f32_e32 v105, v253, v105
	v_cvt_pk_bf16_f32 v96, v96, v97
	v_add_f32_e32 v104, v106, v104
	v_add_f32_e32 v105, v107, v105
	v_cvt_pk_bf16_f32 v106, v106, v107
	v_add_f32_e32 v104, v124, v104
	v_add_f32_e32 v105, v125, v105
	v_mfma_f32_32x32x16_bf16 v[48:63], v[172:175], v[108:111], v[48:63]
	v_add_f32_e64 v104, v126, v104
	v_add_f32_e64 v105, v127, v105
	v_cvt_pk_bf16_f32 v107, v126, v127
	v_add_f32_e64 v104, v234, v104
	v_add_f32_e64 v105, v235, v105
	v_cvt_pk_bf16_f32 v97, v98, v99
	v_add_f32_e32 v112, v104, v105
	v_cvt_pk_bf16_f32 v104, v120, v121
	v_cvt_pk_bf16_f32 v105, v122, v123
	v_cvt_pk_bf16_f32 v98, v100, v101
	v_cvt_pk_bf16_f32 v99, v102, v103
	v_mfma_f32_32x32x16_bf16 v[0:15], v[184:187], v[104:107], v[0:15]
	v_cvt_pk_bf16_f32 v100, v250, v251
	v_cvt_pk_bf16_f32 v101, v252, v253
	v_cvt_pk_bf16_f32 v102, v124, v125
	v_cvt_pk_bf16_f32 v103, v234, v235
	v_add_u32_e32 v126, 0x2200, v249
	s_add_i32 s8, s8, 0x8000
	v_lshl_add_u64 v[204:205], v[204:205], 0, s[70:71]
	v_mfma_f32_32x32x16_bf16 v[48:63], v[168:171], v[104:107], v[48:63]
	v_lshl_add_u64 v[206:207], v[206:207], 0, s[94:95]
	v_lshl_add_u64 v[208:209], v[208:209], 0, s[94:95]
	s_cmp_lg_u32 s8, 0x118000
	v_mfma_f32_32x32x16_bf16 v[0:15], v[180:183], v[96:99], v[0:15]
	v_mfma_f32_32x32x16_bf16 v[48:63], v[164:167], v[96:99], v[48:63]
	v_mfma_f32_32x32x16_bf16 v[0:15], v[176:179], v[100:103], v[0:15]
	v_mfma_f32_32x32x16_bf16 v[48:63], v[160:163], v[100:103], v[48:63]
	ds_read_b64 v[176:177], v126
	ds_read_b64 v[178:179], v126 offset:16
	ds_read_b64 v[172:173], v126 offset:32
	ds_read_b64 v[174:175], v126 offset:48
	ds_read_b64 v[168:169], v126 offset:64
	ds_read_b64 v[170:171], v126 offset:80
	ds_read_b64 v[164:165], v126 offset:96
	ds_read_b64 v[166:167], v126 offset:112
	ds_read_b64 v[160:161], v126 offset:0x1100
	ds_read_b64 v[162:163], v126 offset:0x1110
	ds_read_b64 v[122:123], v126 offset:0x1120
	ds_read_b64 v[124:125], v126 offset:0x1130
	ds_read_b64 v[118:119], v126 offset:0x1140
	ds_read_b64 v[120:121], v126 offset:0x1150
	ds_read_b64 v[114:115], v126 offset:0x1160
	ds_read_b64 v[116:117], v126 offset:0x1170
	s_nop 0
	s_nop 0
	s_waitcnt lgkmcnt(14)
	v_mfma_f32_32x32x16_bf16 v[32:47], v[176:179], v[108:111], v[32:47]
	s_waitcnt lgkmcnt(6)
	v_mfma_f32_32x32x16_bf16 v[16:31], v[160:163], v[108:111], v[16:31]
	v_add_f32_e64 v160, v213, v112
	v_mfma_f32_32x32x16_bf16 v[32:47], v[172:175], v[104:107], v[32:47]
	s_waitcnt lgkmcnt(4)
	v_mfma_f32_32x32x16_bf16 v[16:31], v[122:125], v[104:107], v[16:31]
	v_mfma_f32_32x32x16_bf16 v[32:47], v[168:171], v[96:99], v[32:47]
	s_waitcnt lgkmcnt(2)
	v_mfma_f32_32x32x16_bf16 v[16:31], v[118:121], v[96:99], v[16:31]
	v_mfma_f32_32x32x16_bf16 v[32:47], v[164:167], v[100:103], v[32:47]
	s_waitcnt lgkmcnt(0)
	v_mfma_f32_32x32x16_bf16 v[16:31], v[114:117], v[100:103], v[16:31]
	v_mov_b32_e32 v211, v160
	s_cbranch_scc1 .LBB0_975
